# GEMM accumulator zeroing: 63 v_mov_b64 pairs per tile instead of 126 v_mov_b32 (5 GEMM sites), on top of v86
# speedup vs baseline: 1.0049x; 1.0049x over previous
; template <class Epi, class Sched, bool ALIGN_EPI = false, bool SP2 = false>
; __device__ __forceinline__ void gemm_phase(PG8_LAS unsigned char* lds, const Gemm g, const Sched& S, const Epi& E) {
;     ...
;     Unit cur, nxt; int ui = 0;
;     if (!S.next(0, cur)) return;
;     f32x4 acc[2][2][4][2];
; #pragma unroll
;     for (int a = 0; a < 2; ++a)
; #pragma unroll
;         for (int b = 0; b < 2; ++b)
; #pragma unroll
;             for (int m = 0; m < 4; ++m)
; #pragma unroll
;                 for (int n = 0; n < 2; ++n) acc[a][b][m][n] = (f32x4){0.f, 0.f, 0.f, 0.f};
;     ...
;         const bool has_next = S.next(ui + 1, nxt);
;         const char* nA = has_next ? (const char*)g.A + (size_t)nxt.pm * tstep : cA; const char* nB = has_next ? (const char*)g.Bt + (size_t)nxt.pn * tstep : cB;
;         for (int t = 0; t < nt; t += 2) {
;             const bool last = (t == nt - 2);
;             const char* a1 = cA + (size_t)(t + 1) * kstep;
;             const char* a2 = last ? nA : cA + (size_t)(t + 2) * kstep; const char* b2 = last ? nB : cB + (size_t)(t + 2) * kstep;
;             const char* a3 = a2 + kstep; const char* b3 = b2 + kstep;
.LBB0_144:
	s_ashr_i32 s31, s30, 31
	s_lshl_b64 s[34:35], s[30:31], 19
	s_add_u32 s34, s5, s34
	s_addc_u32 s35, s18, s35
	s_and_b64 s[36:37], s[40:41], exec
	s_cselect_b32 s31, s35, s91
	s_cselect_b32 s43, s34, s90
	s_ashr_i32 s29, s28, 31
	s_lshl_b64 s[36:37], s[28:29], 19
	s_add_u32 s36, s19, s36
	s_addc_u32 s37, s44, s37
	s_and_b64 s[46:47], s[40:41], exec
	s_cselect_b32 s29, s37, s51
	s_cselect_b32 s62, s36, s50
	s_add_u32 s90, s90, 0x40080
	s_addc_u32 s91, s91, 0
	s_add_u32 s63, s50, 0x100
	v_mov_b32_e32 v0, 0
	s_addc_u32 s64, s51, 0
	s_mov_b32 s65, -2
	v_mov_b32_e32 v1, v0
	v_mov_b64_e32 v[2:3], 0
	v_mov_b64_e32 v[4:5], 0
	v_mov_b64_e32 v[6:7], 0
	v_mov_b64_e32 v[12:13], 0
	v_mov_b64_e32 v[14:15], 0
	v_mov_b64_e32 v[20:21], 0
	v_mov_b64_e32 v[22:23], 0
	v_mov_b64_e32 v[28:29], 0
	v_mov_b64_e32 v[30:31], 0
	v_mov_b64_e32 v[38:39], 0
	v_mov_b64_e32 v[40:41], 0
	v_mov_b64_e32 v[46:47], 0
	v_mov_b64_e32 v[48:49], 0
	v_mov_b64_e32 v[54:55], 0
	v_mov_b64_e32 v[56:57], 0
	v_mov_b64_e32 v[8:9], 0
	v_mov_b64_e32 v[10:11], 0
	v_mov_b64_e32 v[16:17], 0
	v_mov_b64_e32 v[18:19], 0
	v_mov_b64_e32 v[24:25], 0
	v_mov_b64_e32 v[26:27], 0
	v_mov_b64_e32 v[34:35], 0
	v_mov_b64_e32 v[36:37], 0
	v_mov_b64_e32 v[42:43], 0
	v_mov_b64_e32 v[44:45], 0
	v_mov_b64_e32 v[50:51], 0
	v_mov_b64_e32 v[52:53], 0
	v_mov_b64_e32 v[58:59], 0
	v_mov_b64_e32 v[60:61], 0
	v_mov_b64_e32 v[62:63], 0
	v_mov_b64_e32 v[64:65], 0
	v_mov_b64_e32 v[66:67], 0
	v_mov_b64_e32 v[68:69], 0
	v_mov_b64_e32 v[70:71], 0
	v_mov_b64_e32 v[72:73], 0
	v_mov_b64_e32 v[78:79], 0
	v_mov_b64_e32 v[80:81], 0
	v_mov_b64_e32 v[86:87], 0
	v_mov_b64_e32 v[88:89], 0
	v_mov_b64_e32 v[94:95], 0
	v_mov_b64_e32 v[96:97], 0
	v_mov_b64_e32 v[102:103], 0
	v_mov_b64_e32 v[104:105], 0
	v_mov_b64_e32 v[110:111], 0
	v_mov_b64_e32 v[112:113], 0
	v_mov_b64_e32 v[118:119], 0
	v_mov_b64_e32 v[120:121], 0
	v_mov_b64_e32 v[74:75], 0
	v_mov_b64_e32 v[76:77], 0
	v_mov_b64_e32 v[82:83], 0
	v_mov_b64_e32 v[84:85], 0
	v_mov_b64_e32 v[90:91], 0
	v_mov_b64_e32 v[92:93], 0
	v_mov_b64_e32 v[98:99], 0
	v_mov_b64_e32 v[100:101], 0
	v_mov_b64_e32 v[106:107], 0
	v_mov_b64_e32 v[108:109], 0
	v_mov_b64_e32 v[114:115], 0
	v_mov_b64_e32 v[116:117], 0
	v_mov_b64_e32 v[122:123], 0
	v_mov_b64_e32 v[124:125], 0
	v_mov_b64_e32 v[126:127], 0
	v_mov_b64_e32 v[128:129], 0

; template <class Epi, class Sched, bool ALIGN_EPI = false, bool SP2 = false>
; __device__ __forceinline__ void gemm_phase(PG8_LAS unsigned char* lds, const Gemm g, const Sched& S, const Epi& E) {
;     ...
;     Unit cur, nxt; int ui = 0;
;     if (!S.next(0, cur)) return;
;     f32x4 acc[2][2][4][2];
; #pragma unroll
;     for (int a = 0; a < 2; ++a)
; #pragma unroll
;         for (int b = 0; b < 2; ++b)
; #pragma unroll
;             for (int m = 0; m < 4; ++m)
; #pragma unroll
;                 for (int n = 0; n < 2; ++n) acc[a][b][m][n] = (f32x4){0.f, 0.f, 0.f, 0.f};
;     ...
;         const bool has_next = S.next(ui + 1, nxt);
;         const char* nA = has_next ? (const char*)g.A + (size_t)nxt.pm * tstep : cA; const char* nB = has_next ? (const char*)g.Bt + (size_t)nxt.pn * tstep : cB;
;         for (int t = 0; t < nt; t += 2) {
;             const bool last = (t == nt - 2);
;             const char* a1 = cA + (size_t)(t + 1) * kstep;
;             const char* a2 = last ? nA : cA + (size_t)(t + 2) * kstep; const char* b2 = last ? nB : cB + (size_t)(t + 2) * kstep;
;             const char* a3 = a2 + kstep; const char* b3 = b2 + kstep;
.LBB0_548:
	s_ashr_i32 s91, s90, 31
	s_lshl_b64 s[6:7], s[90:91], 19
	s_add_u32 s46, s19, s6
	s_addc_u32 s47, s44, s7
	s_and_b64 s[6:7], s[40:41], exec
	s_cselect_b32 s35, s47, s37
	s_cselect_b32 s62, s46, s36
	s_ashr_i32 s43, s42, 31
	s_lshl_b64 s[6:7], s[42:43], 19
	s_add_u32 s6, s45, s6
	s_addc_u32 s7, s55, s7
	s_and_b64 s[64:65], s[40:41], exec
	s_cselect_b32 s43, s7, s51
	s_cselect_b32 s63, s6, s50
	s_add_u32 vcc_lo, s36, 0x40080
	s_addc_u32 vcc_hi, s37, 0
	s_add_u32 s64, s50, 0x100
	v_mov_b32_e32 v0, 0
	s_addc_u32 s65, s51, 0
	s_mov_b32 s91, -2
	v_mov_b32_e32 v1, v0
	v_mov_b64_e32 v[2:3], 0
	v_mov_b64_e32 v[8:9], 0
	v_mov_b64_e32 v[10:11], 0
	v_mov_b64_e32 v[16:17], 0
	v_mov_b64_e32 v[18:19], 0
	v_mov_b64_e32 v[24:25], 0
	v_mov_b64_e32 v[26:27], 0
	v_mov_b64_e32 v[34:35], 0
	v_mov_b64_e32 v[36:37], 0
	v_mov_b64_e32 v[42:43], 0
	v_mov_b64_e32 v[44:45], 0
	v_mov_b64_e32 v[50:51], 0
	v_mov_b64_e32 v[52:53], 0
	v_mov_b64_e32 v[58:59], 0
	v_mov_b64_e32 v[60:61], 0
	v_mov_b64_e32 v[4:5], 0
	v_mov_b64_e32 v[6:7], 0
	v_mov_b64_e32 v[12:13], 0
	v_mov_b64_e32 v[14:15], 0
	v_mov_b64_e32 v[20:21], 0
	v_mov_b64_e32 v[22:23], 0
	v_mov_b64_e32 v[28:29], 0
	v_mov_b64_e32 v[30:31], 0
	v_mov_b64_e32 v[38:39], 0
	v_mov_b64_e32 v[40:41], 0
	v_mov_b64_e32 v[46:47], 0
	v_mov_b64_e32 v[48:49], 0
	v_mov_b64_e32 v[54:55], 0
	v_mov_b64_e32 v[56:57], 0
	v_mov_b64_e32 v[62:63], 0
	v_mov_b64_e32 v[64:65], 0
	v_mov_b64_e32 v[66:67], 0
	v_mov_b64_e32 v[68:69], 0
	v_mov_b64_e32 v[74:75], 0
	v_mov_b64_e32 v[76:77], 0
	v_mov_b64_e32 v[82:83], 0
	v_mov_b64_e32 v[84:85], 0
	v_mov_b64_e32 v[90:91], 0
	v_mov_b64_e32 v[92:93], 0
	v_mov_b64_e32 v[98:99], 0
	v_mov_b64_e32 v[100:101], 0
	v_mov_b64_e32 v[106:107], 0
	v_mov_b64_e32 v[108:109], 0
	v_mov_b64_e32 v[114:115], 0
	v_mov_b64_e32 v[116:117], 0
	v_mov_b64_e32 v[122:123], 0
	v_mov_b64_e32 v[124:125], 0
	v_mov_b64_e32 v[70:71], 0
	v_mov_b64_e32 v[72:73], 0
	v_mov_b64_e32 v[78:79], 0
	v_mov_b64_e32 v[80:81], 0
	v_mov_b64_e32 v[86:87], 0
	v_mov_b64_e32 v[88:89], 0
	v_mov_b64_e32 v[94:95], 0
	v_mov_b64_e32 v[96:97], 0
	v_mov_b64_e32 v[102:103], 0
	v_mov_b64_e32 v[104:105], 0
	v_mov_b64_e32 v[110:111], 0
	v_mov_b64_e32 v[112:113], 0
	v_mov_b64_e32 v[118:119], 0
	v_mov_b64_e32 v[120:121], 0
	v_mov_b64_e32 v[126:127], 0
	v_mov_b64_e32 v[128:129], 0

; #define PG8_STAGE(bufoff, gbase, voff) do { _Pragma("unroll") for (int _i = 0; _i < 2; ++_i) \
;         __builtin_amdgcn_global_load_lds((const unsigned*)((const char*)(gbase) + (voff)[_i]), (PG8_LAS unsigned*)(lds + (bufoff) + ldsw + _i * 8192), 16, 0, 0); } while (0)
; #define PG8_LDA(dst, b, h) do { _Pragma("unroll") for (int m = 0; m < 4; ++m) _Pragma("unroll") for (int k = 0; k < 2; ++k) dst[m][k] = *(const PG8_LAS bf16x8*)(lds + PG8_SA(b, h) + aoff + m * 2048 + k * 1024); } while (0)
; #define PG8_LDB(dst, b, h) do { _Pragma("unroll") for (int n = 0; n < 2; ++n) _Pragma("unroll") for (int k = 0; k < 2; ++k) dst[n][k] = *(const PG8_LAS bf16x8*)(lds + PG8_SB(b, h) + boff + n * 2048 + k * 1024); } while (0)
; #define PG8_MMA(ai, bj, At, Bt) do { __builtin_amdgcn_s_setprio(1); _Pragma("unroll") for (int m = 0; m < 4; ++m) _Pragma("unroll") for (int n = 0; n < 2; ++n) _Pragma("unroll") for (int k = 0; k < 2; ++k) \
;         acc[ai][bj][m][n] = __builtin_amdgcn_mfma_f32_16x16x32_bf16(Bt[n][k], At[m][k], acc[ai][bj][m][n], 0, 0, 0); __builtin_amdgcn_s_setprio(0); } while (0)
; #define PG8_WAIT_V(n) asm volatile("s_waitcnt vmcnt(" #n ")" ::: "memory")
; #define PG8_WAIT_L(n) asm volatile("s_waitcnt lgkmcnt(" #n ")" ::: "memory")
; #define PG8_BAR __builtin_amdgcn_s_barrier()
; #define PG8_SCHED __builtin_amdgcn_sched_barrier(0)
; template <class Epi, class Sched, bool ALIGN_EPI = false, bool SP2 = false>
; __device__ __forceinline__ void gemm_phase(PG8_LAS unsigned char* lds, const Gemm g, const Sched& S, const Epi& E) {
;     ...
;             PG8_LDB(B0, 0, 0); PG8_LDB(B1, 0, 1); PG8_SCHED; PG8_LDA(At, 0, 0); PG8_STAGE(PG8_SA(1, 1), a1 + hstep, voffA);
;             PG8_WAIT_V(8); PG8_WAIT_L(0); PG8_BAR; PG8_MMA(0, 0, At, B0); PG8_MMA(0, 1, At, B1); PG8_BAR; PG8_SCHED;
;             PG8_LDA(At, 0, 1); PG8_STAGE(PG8_SB(0, 0), b2, voffB); PG8_STAGE(PG8_SB(0, 1), b2 + hstep, voffB); PG8_STAGE(PG8_SA(0, 0), a2, voffA);
;             PG8_WAIT_V(8); PG8_WAIT_L(0); PG8_BAR; PG8_MMA(1, 0, At, B0); PG8_MMA(1, 1, At, B1); PG8_BAR; PG8_SCHED;
.LBB0_826:
	s_add_i32 s68, s46, 2
	s_add_u32 s69, s30, vcc_lo
	s_addc_u32 s47, s31, vcc_hi
	s_add_u32 s70, s6, vcc_lo
	s_addc_u32 s71, s7, vcc_hi
	s_add_i32 s72, 0, 0x10000
	s_cmp_eq_u32 s63, s46
	s_cselect_b32 s47, s37, s47
	s_cselect_b32 s46, s66, s69
	v_add_u32_e32 v33, s72, v106
	s_cselect_b32 s71, s35, s71
	s_cselect_b32 s70, s67, s70
	s_add_i32 s69, 0, 0x14000
	ds_read_b128 v[116:119], v33
	ds_read_b128 v[148:151], v33 offset:1024
	ds_read_b128 v[152:155], v33 offset:2048
	ds_read_b128 v[156:159], v33 offset:3072
	v_add_u32_e32 v33, s69, v106
	ds_read_b128 v[160:163], v33
	ds_read_b128 v[164:167], v33 offset:1024
	ds_read_b128 v[168:171], v33 offset:2048
	ds_read_b128 v[172:175], v33 offset:3072
	v_lshl_add_u64 v[220:221], s[30:31], 0, v[104:105]
	s_add_i32 m0, s19, 0xc000
	ds_read_b128 v[176:179], v107
	ds_read_b128 v[180:183], v107 offset:1024
	ds_read_b128 v[184:187], v107 offset:2048
	ds_read_b128 v[188:191], v107 offset:3072
	ds_read_b128 v[204:207], v107 offset:4096
	ds_read_b128 v[208:211], v107 offset:5120
	ds_read_b128 v[212:215], v107 offset:6144
	ds_read_b128 v[216:219], v107 offset:7168
	global_load_lds_dwordx4 v[220:221], off
	v_lshl_add_u64 v[220:221], s[30:31], 0, v[34:35]
	s_add_i32 m0, s19, 0xe000
	s_nop 0
	global_load_lds_dwordx4 v[220:221], off
	s_waitcnt vmcnt(8)
	s_waitcnt lgkmcnt(0)
	s_barrier
	s_setprio 1
	s_waitcnt lgkmcnt(0)
	v_mfma_f32_16x16x32_bf16 v[144:147], v[116:119], v[176:179], v[144:147]
	v_mfma_f32_16x16x32_bf16 v[140:143], v[152:155], v[176:179], v[140:143]
	v_mfma_f32_16x16x32_bf16 v[128:131], v[116:119], v[184:187], v[128:131]
	v_mfma_f32_16x16x32_bf16 v[124:127], v[152:155], v[184:187], v[124:127]
	v_mfma_f32_16x16x32_bf16 v[108:111], v[116:119], v[204:207], v[108:111]
	v_mfma_f32_16x16x32_bf16 v[96:99], v[152:155], v[204:207], v[96:99]
	v_mfma_f32_16x16x32_bf16 v[80:83], v[116:119], v[212:215], v[80:83]
	v_mfma_f32_16x16x32_bf16 v[76:79], v[152:155], v[212:215], v[76:79]
	v_mfma_f32_16x16x32_bf16 v[144:147], v[148:151], v[180:183], v[144:147]
	v_mfma_f32_16x16x32_bf16 v[140:143], v[156:159], v[180:183], v[140:143]
	v_mfma_f32_16x16x32_bf16 v[128:131], v[148:151], v[188:191], v[128:131]
	v_mfma_f32_16x16x32_bf16 v[124:127], v[156:159], v[188:191], v[124:127]
	v_mfma_f32_16x16x32_bf16 v[108:111], v[148:151], v[208:211], v[108:111]
	v_mfma_f32_16x16x32_bf16 v[96:99], v[156:159], v[208:211], v[96:99]
	v_mfma_f32_16x16x32_bf16 v[80:83], v[148:151], v[216:219], v[80:83]
	v_mfma_f32_16x16x32_bf16 v[76:79], v[156:159], v[216:219], v[76:79]
	s_setprio 0
	s_setprio 1
	v_mfma_f32_16x16x32_bf16 v[136:139], v[160:163], v[176:179], v[136:139]
	v_mfma_f32_16x16x32_bf16 v[132:135], v[168:171], v[176:179], v[132:135]
	v_mfma_f32_16x16x32_bf16 v[120:123], v[160:163], v[184:187], v[120:123]
	v_mfma_f32_16x16x32_bf16 v[112:115], v[168:171], v[184:187], v[112:115]
	v_mfma_f32_16x16x32_bf16 v[88:91], v[160:163], v[204:207], v[88:91]
	v_mfma_f32_16x16x32_bf16 v[84:87], v[168:171], v[204:207], v[84:87]
	v_mfma_f32_16x16x32_bf16 v[72:75], v[160:163], v[212:215], v[72:75]
	v_mfma_f32_16x16x32_bf16 v[68:71], v[168:171], v[212:215], v[68:71]
	v_mfma_f32_16x16x32_bf16 v[136:139], v[164:167], v[180:183], v[136:139]
	v_mfma_f32_16x16x32_bf16 v[132:135], v[172:175], v[180:183], v[132:135]
	v_mfma_f32_16x16x32_bf16 v[120:123], v[164:167], v[188:191], v[120:123]
	v_mfma_f32_16x16x32_bf16 v[112:115], v[172:175], v[188:191], v[112:115]
	v_mfma_f32_16x16x32_bf16 v[88:91], v[164:167], v[208:211], v[88:91]
	v_mfma_f32_16x16x32_bf16 v[84:87], v[172:175], v[208:211], v[84:87]
	v_mfma_f32_16x16x32_bf16 v[72:75], v[164:167], v[216:219], v[72:75]
	v_mfma_f32_16x16x32_bf16 v[68:71], v[172:175], v[216:219], v[68:71]
	s_setprio 0
	s_barrier
	s_add_i32 s72, s72, s45
	v_lshl_add_u64 v[220:221], s[70:71], 0, v[92:93]
	s_mov_b32 m0, s72
	ds_read_b128 v[176:179], v107 offset:16384
	ds_read_b128 v[180:183], v107 offset:17408
	ds_read_b128 v[184:187], v107 offset:18432
	ds_read_b128 v[188:191], v107 offset:19456
	ds_read_b128 v[204:207], v107 offset:20480
	ds_read_b128 v[208:211], v107 offset:21504
	ds_read_b128 v[212:215], v107 offset:22528
	ds_read_b128 v[216:219], v107 offset:23552
	global_load_lds_dwordx4 v[220:221], off
	s_add_i32 m0, s72, 0x2000
	v_lshl_add_u64 v[222:223], s[70:71], 0, v[94:95]
	s_add_u32 s70, s70, s17
	s_addc_u32 s71, s71, 0
	s_add_i32 s69, s69, s45
	global_load_lds_dwordx4 v[222:223], off
	v_lshl_add_u64 v[224:225], s[70:71], 0, v[92:93]
	s_mov_b32 m0, s69
	v_lshl_add_u64 v[226:227], s[70:71], 0, v[94:95]
	global_load_lds_dwordx4 v[224:225], off
	s_add_i32 m0, s69, 0x2000
	v_lshl_add_u64 v[238:239], s[46:47], 0, v[92:93]
	global_load_lds_dwordx4 v[226:227], off
	s_mov_b32 m0, s19
	v_lshl_add_u64 v[240:241], s[46:47], 0, v[94:95]
	global_load_lds_dwordx4 v[238:239], off
	s_mov_b32 m0, s57
	s_nop 0
	global_load_lds_dwordx4 v[240:241], off
	s_waitcnt vmcnt(8)
	s_waitcnt lgkmcnt(0)
	s_barrier
; #define PG8_STAGE(bufoff, gbase, voff) do { _Pragma("unroll") for (int _i = 0; _i < 2; ++_i) \
;         __builtin_amdgcn_global_load_lds((const unsigned*)((const char*)(gbase) + (voff)[_i]), (PG8_LAS unsigned*)(lds + (bufoff) + ldsw + _i * 8192), 16, 0, 0); } while (0)
; #define PG8_LDA(dst, b, h) do { _Pragma("unroll") for (int m = 0; m < 4; ++m) _Pragma("unroll") for (int k = 0; k < 2; ++k) dst[m][k] = *(const PG8_LAS bf16x8*)(lds + PG8_SA(b, h) + aoff + m * 2048 + k * 1024); } while (0)
; #define PG8_LDB(dst, b, h) do { _Pragma("unroll") for (int n = 0; n < 2; ++n) _Pragma("unroll") for (int k = 0; k < 2; ++k) dst[n][k] = *(const PG8_LAS bf16x8*)(lds + PG8_SB(b, h) + boff + n * 2048 + k * 1024); } while (0)
; #define PG8_MMA(ai, bj, At, Bt) do { __builtin_amdgcn_s_setprio(1); _Pragma("unroll") for (int m = 0; m < 4; ++m) _Pragma("unroll") for (int n = 0; n < 2; ++n) _Pragma("unroll") for (int k = 0; k < 2; ++k) \
;         acc[ai][bj][m][n] = __builtin_amdgcn_mfma_f32_16x16x32_bf16(Bt[n][k], At[m][k], acc[ai][bj][m][n], 0, 0, 0); __builtin_amdgcn_s_setprio(0); } while (0)
; #define PG8_WAIT_V(n) asm volatile("s_waitcnt vmcnt(" #n ")" ::: "memory")
; #define PG8_WAIT_L(n) asm volatile("s_waitcnt lgkmcnt(" #n ")" ::: "memory")
; #define PG8_BAR __builtin_amdgcn_s_barrier()
; #define PG8_SCHED __builtin_amdgcn_sched_barrier(0)
; template <class Epi, class Sched, bool ALIGN_EPI = false, bool SP2 = false>
; __device__ __forceinline__ void gemm_phase(PG8_LAS unsigned char* lds, const Gemm g, const Sched& S, const Epi& E) {
;     ...
;             PG8_WAIT_V(8); PG8_WAIT_L(0); PG8_BAR; PG8_MMA(1, 0, At, B0); PG8_MMA(1, 1, At, B1); PG8_BAR; PG8_SCHED;
;             PG8_LDB(B0, 1, 0); PG8_LDB(B1, 1, 1); PG8_SCHED; PG8_LDA(At, 1, 0); PG8_STAGE(PG8_SA(0, 1), a2 + hstep, voffA);
;             PG8_WAIT_V(8); PG8_WAIT_L(0); PG8_BAR; PG8_MMA(0, 0, At, B0); PG8_MMA(0, 1, At, B1); PG8_BAR; PG8_SCHED;
	s_setprio 1
	s_waitcnt lgkmcnt(0)
	v_mfma_f32_16x16x32_bf16 v[64:67], v[116:119], v[176:179], v[64:67]
	v_mfma_f32_16x16x32_bf16 v[60:63], v[152:155], v[176:179], v[60:63]
	v_mfma_f32_16x16x32_bf16 v[48:51], v[116:119], v[184:187], v[48:51]
	v_mfma_f32_16x16x32_bf16 v[44:47], v[152:155], v[184:187], v[44:47]
	v_mfma_f32_16x16x32_bf16 v[28:31], v[116:119], v[204:207], v[28:31]
	v_mfma_f32_16x16x32_bf16 v[24:27], v[152:155], v[204:207], v[24:27]
	v_mfma_f32_16x16x32_bf16 v[12:15], v[116:119], v[212:215], v[12:15]
	v_mfma_f32_16x16x32_bf16 v[8:11], v[152:155], v[212:215], v[8:11]
	v_mfma_f32_16x16x32_bf16 v[64:67], v[148:151], v[180:183], v[64:67]
	v_mfma_f32_16x16x32_bf16 v[60:63], v[156:159], v[180:183], v[60:63]
	v_mfma_f32_16x16x32_bf16 v[48:51], v[148:151], v[188:191], v[48:51]
	v_mfma_f32_16x16x32_bf16 v[44:47], v[156:159], v[188:191], v[44:47]
	v_mfma_f32_16x16x32_bf16 v[28:31], v[148:151], v[208:211], v[28:31]
	v_mfma_f32_16x16x32_bf16 v[24:27], v[156:159], v[208:211], v[24:27]
	v_mfma_f32_16x16x32_bf16 v[12:15], v[148:151], v[216:219], v[12:15]
	v_mfma_f32_16x16x32_bf16 v[8:11], v[156:159], v[216:219], v[8:11]
	s_setprio 0
	s_setprio 1
	v_mfma_f32_16x16x32_bf16 v[56:59], v[160:163], v[176:179], v[56:59]
	v_mfma_f32_16x16x32_bf16 v[52:55], v[168:171], v[176:179], v[52:55]
	v_mfma_f32_16x16x32_bf16 v[40:43], v[160:163], v[184:187], v[40:43]
	v_mfma_f32_16x16x32_bf16 v[36:39], v[168:171], v[184:187], v[36:39]
	v_mfma_f32_16x16x32_bf16 v[20:23], v[160:163], v[204:207], v[20:23]
	v_mfma_f32_16x16x32_bf16 v[16:19], v[168:171], v[204:207], v[16:19]
	v_mfma_f32_16x16x32_bf16 v[4:7], v[160:163], v[212:215], v[4:7]
	v_mfma_f32_16x16x32_bf16 v[0:3], v[168:171], v[212:215], v[0:3]
	v_mfma_f32_16x16x32_bf16 v[56:59], v[164:167], v[180:183], v[56:59]
	v_mfma_f32_16x16x32_bf16 v[52:55], v[172:175], v[180:183], v[52:55]
	v_mfma_f32_16x16x32_bf16 v[40:43], v[164:167], v[188:191], v[40:43]
	v_mfma_f32_16x16x32_bf16 v[36:39], v[172:175], v[188:191], v[36:39]
	v_mfma_f32_16x16x32_bf16 v[20:23], v[164:167], v[208:211], v[20:23]
	v_mfma_f32_16x16x32_bf16 v[16:19], v[172:175], v[208:211], v[16:19]
	v_mfma_f32_16x16x32_bf16 v[4:7], v[164:167], v[216:219], v[4:7]
	v_mfma_f32_16x16x32_bf16 v[0:3], v[172:175], v[216:219], v[0:3]
	s_setprio 0
	s_barrier
	s_add_i32 s69, 0, 0x18000
	v_add_u32_e32 v33, s69, v106
	s_add_i32 s70, 0, 0x1c000
	ds_read_b128 v[116:119], v33
	ds_read_b128 v[148:151], v33 offset:1024
	ds_read_b128 v[152:155], v33 offset:2048
	ds_read_b128 v[156:159], v33 offset:3072
	v_add_u32_e32 v33, s70, v106
	ds_read_b128 v[160:163], v33
	ds_read_b128 v[164:167], v33 offset:1024
	ds_read_b128 v[168:171], v33 offset:2048
	ds_read_b128 v[172:175], v33 offset:3072
	s_add_u32 s46, s46, s17
	s_addc_u32 s47, s47, 0
	s_mov_b32 m0, s58
	v_lshl_add_u64 v[242:243], s[46:47], 0, v[92:93]
	ds_read_b128 v[176:179], v107 offset:32768
	ds_read_b128 v[180:183], v107 offset:33792
	ds_read_b128 v[184:187], v107 offset:34816
	ds_read_b128 v[188:191], v107 offset:35840
	ds_read_b128 v[204:207], v107 offset:36864
	ds_read_b128 v[208:211], v107 offset:37888
	ds_read_b128 v[212:215], v107 offset:38912
	ds_read_b128 v[216:219], v107 offset:39936
	global_load_lds_dwordx4 v[242:243], off
	v_lshl_add_u64 v[242:243], s[46:47], 0, v[94:95]
	s_mov_b32 m0, s59
	s_nop 0
	global_load_lds_dwordx4 v[242:243], off
	s_waitcnt vmcnt(8)
	s_waitcnt lgkmcnt(0)
	s_barrier
	s_setprio 1
	s_waitcnt lgkmcnt(0)
	v_mfma_f32_16x16x32_bf16 v[144:147], v[116:119], v[176:179], v[144:147]
	v_mfma_f32_16x16x32_bf16 v[140:143], v[152:155], v[176:179], v[140:143]
	v_mfma_f32_16x16x32_bf16 v[128:131], v[116:119], v[184:187], v[128:131]
	v_mfma_f32_16x16x32_bf16 v[124:127], v[152:155], v[184:187], v[124:127]
	v_mfma_f32_16x16x32_bf16 v[108:111], v[116:119], v[204:207], v[108:111]
	v_mfma_f32_16x16x32_bf16 v[96:99], v[152:155], v[204:207], v[96:99]
	v_mfma_f32_16x16x32_bf16 v[80:83], v[116:119], v[212:215], v[80:83]
	v_mfma_f32_16x16x32_bf16 v[76:79], v[152:155], v[212:215], v[76:79]
	v_mfma_f32_16x16x32_bf16 v[144:147], v[148:151], v[180:183], v[144:147]
	v_mfma_f32_16x16x32_bf16 v[140:143], v[156:159], v[180:183], v[140:143]
	v_mfma_f32_16x16x32_bf16 v[128:131], v[148:151], v[188:191], v[128:131]
	v_mfma_f32_16x16x32_bf16 v[124:127], v[156:159], v[188:191], v[124:127]
	v_mfma_f32_16x16x32_bf16 v[108:111], v[148:151], v[208:211], v[108:111]
	v_mfma_f32_16x16x32_bf16 v[96:99], v[156:159], v[208:211], v[96:99]
	v_mfma_f32_16x16x32_bf16 v[80:83], v[148:151], v[216:219], v[80:83]
	v_mfma_f32_16x16x32_bf16 v[76:79], v[156:159], v[216:219], v[76:79]
	s_setprio 0
	s_setprio 1
	v_mfma_f32_16x16x32_bf16 v[136:139], v[160:163], v[176:179], v[136:139]
	v_mfma_f32_16x16x32_bf16 v[132:135], v[168:171], v[176:179], v[132:135]
	v_mfma_f32_16x16x32_bf16 v[120:123], v[160:163], v[184:187], v[120:123]
	v_mfma_f32_16x16x32_bf16 v[112:115], v[168:171], v[184:187], v[112:115]
	v_mfma_f32_16x16x32_bf16 v[88:91], v[160:163], v[204:207], v[88:91]
	v_mfma_f32_16x16x32_bf16 v[84:87], v[168:171], v[204:207], v[84:87]
	v_mfma_f32_16x16x32_bf16 v[72:75], v[160:163], v[212:215], v[72:75]
	v_mfma_f32_16x16x32_bf16 v[68:71], v[168:171], v[212:215], v[68:71]
	v_mfma_f32_16x16x32_bf16 v[136:139], v[164:167], v[180:183], v[136:139]
	v_mfma_f32_16x16x32_bf16 v[132:135], v[172:175], v[180:183], v[132:135]
	v_mfma_f32_16x16x32_bf16 v[120:123], v[164:167], v[188:191], v[120:123]
	v_mfma_f32_16x16x32_bf16 v[112:115], v[172:175], v[188:191], v[112:115]
	v_mfma_f32_16x16x32_bf16 v[88:91], v[164:167], v[208:211], v[88:91]
	v_mfma_f32_16x16x32_bf16 v[84:87], v[172:175], v[208:211], v[84:87]
	v_mfma_f32_16x16x32_bf16 v[72:75], v[164:167], v[216:219], v[72:75]
	v_mfma_f32_16x16x32_bf16 v[68:71], v[172:175], v[216:219], v[68:71]
	s_setprio 0
	s_barrier
; #define PG8_STAGE(bufoff, gbase, voff) do { _Pragma("unroll") for (int _i = 0; _i < 2; ++_i) \
;         __builtin_amdgcn_global_load_lds((const unsigned*)((const char*)(gbase) + (voff)[_i]), (PG8_LAS unsigned*)(lds + (bufoff) + ldsw + _i * 8192), 16, 0, 0); } while (0)
; #define PG8_LDA(dst, b, h) do { _Pragma("unroll") for (int m = 0; m < 4; ++m) _Pragma("unroll") for (int k = 0; k < 2; ++k) dst[m][k] = *(const PG8_LAS bf16x8*)(lds + PG8_SA(b, h) + aoff + m * 2048 + k * 1024); } while (0)
; #define PG8_MMA(ai, bj, At, Bt) do { __builtin_amdgcn_s_setprio(1); _Pragma("unroll") for (int m = 0; m < 4; ++m) _Pragma("unroll") for (int n = 0; n < 2; ++n) _Pragma("unroll") for (int k = 0; k < 2; ++k) \
;         acc[ai][bj][m][n] = __builtin_amdgcn_mfma_f32_16x16x32_bf16(Bt[n][k], At[m][k], acc[ai][bj][m][n], 0, 0, 0); __builtin_amdgcn_s_setprio(0); } while (0)
; #define PG8_WAIT_V(n) asm volatile("s_waitcnt vmcnt(" #n ")" ::: "memory")
; #define PG8_WAIT_L(n) asm volatile("s_waitcnt lgkmcnt(" #n ")" ::: "memory")
; #define PG8_BAR __builtin_amdgcn_s_barrier()
; #define PG8_SCHED __builtin_amdgcn_sched_barrier(0)
; template <class Epi, class Sched, bool ALIGN_EPI = false, bool SP2 = false>
; __device__ __forceinline__ void gemm_phase(PG8_LAS unsigned char* lds, const Gemm g, const Sched& S, const Epi& E) {
;     ...
;             PG8_LDA(At, 1, 1); PG8_STAGE(PG8_SB(1, 0), b3, voffB); PG8_STAGE(PG8_SB(1, 1), b3 + hstep, voffB); PG8_STAGE(PG8_SA(1, 0), a3, voffA);
;             PG8_WAIT_V(8); PG8_WAIT_L(0); PG8_BAR; PG8_MMA(1, 0, At, B0); PG8_MMA(1, 1, At, B1); PG8_BAR; PG8_SCHED;
;     ...
;         if (!has_next) break;
; #pragma unroll
;         for (int a = 0; a < 2; ++a)
; #pragma unroll
;             for (int b = 0; b < 2; ++b)
; #pragma unroll
;                 for (int m = 0; m < 4; ++m)
; #pragma unroll
;                     for (int n = 0; n < 2; ++n) acc[a][b][m][n] = (f32x4){0.f, 0.f, 0.f, 0.f};
;         cur = nxt; cA = nA; cB = nB; ++ui;
;         if constexpr (ALIGN_EPI) { if (wr == 1) PG8_BAR; }
	s_add_i32 s46, s69, s45
	v_lshl_add_u64 v[220:221], v[220:221], 0, s[8:9]
	s_mov_b32 m0, s46
	ds_read_b128 v[176:179], v107 offset:49152
	ds_read_b128 v[180:183], v107 offset:50176
	ds_read_b128 v[184:187], v107 offset:51200
	ds_read_b128 v[188:191], v107 offset:52224
	ds_read_b128 v[204:207], v107 offset:53248
	ds_read_b128 v[208:211], v107 offset:54272
	ds_read_b128 v[212:215], v107 offset:55296
	ds_read_b128 v[216:219], v107 offset:56320
	global_load_lds_dwordx4 v[220:221], off
	v_lshl_add_u64 v[220:221], v[222:223], 0, s[8:9]
	s_add_i32 m0, s46, 0x2000
	s_add_i32 s46, s70, s45
	global_load_lds_dwordx4 v[220:221], off
	v_lshl_add_u64 v[220:221], v[224:225], 0, s[8:9]
	s_mov_b32 m0, s46
	s_nop 0
	global_load_lds_dwordx4 v[220:221], off
	v_lshl_add_u64 v[220:221], v[226:227], 0, s[8:9]
	s_add_i32 m0, s46, 0x2000
	s_nop 0
	global_load_lds_dwordx4 v[220:221], off
	v_lshl_add_u64 v[220:221], v[238:239], 0, s[8:9]
	s_mov_b32 m0, s60
	s_nop 0
	global_load_lds_dwordx4 v[220:221], off
	v_lshl_add_u64 v[220:221], v[240:241], 0, s[8:9]
	s_mov_b32 m0, s61
	s_nop 0
	global_load_lds_dwordx4 v[220:221], off
	s_waitcnt vmcnt(8)
	s_waitcnt lgkmcnt(0)
	s_barrier
	s_setprio 1
	s_waitcnt lgkmcnt(0)
	v_mfma_f32_16x16x32_bf16 v[64:67], v[116:119], v[176:179], v[64:67]
	v_mfma_f32_16x16x32_bf16 v[60:63], v[152:155], v[176:179], v[60:63]
	v_mfma_f32_16x16x32_bf16 v[48:51], v[116:119], v[184:187], v[48:51]
	v_mfma_f32_16x16x32_bf16 v[44:47], v[152:155], v[184:187], v[44:47]
	v_mfma_f32_16x16x32_bf16 v[28:31], v[116:119], v[204:207], v[28:31]
	v_mfma_f32_16x16x32_bf16 v[24:27], v[152:155], v[204:207], v[24:27]
	v_mfma_f32_16x16x32_bf16 v[12:15], v[116:119], v[212:215], v[12:15]
	v_mfma_f32_16x16x32_bf16 v[8:11], v[152:155], v[212:215], v[8:11]
	v_mfma_f32_16x16x32_bf16 v[64:67], v[148:151], v[180:183], v[64:67]
	v_mfma_f32_16x16x32_bf16 v[60:63], v[156:159], v[180:183], v[60:63]
	v_mfma_f32_16x16x32_bf16 v[48:51], v[148:151], v[188:191], v[48:51]
	v_mfma_f32_16x16x32_bf16 v[44:47], v[156:159], v[188:191], v[44:47]
	v_mfma_f32_16x16x32_bf16 v[28:31], v[148:151], v[208:211], v[28:31]
	v_mfma_f32_16x16x32_bf16 v[24:27], v[156:159], v[208:211], v[24:27]
	v_mfma_f32_16x16x32_bf16 v[12:15], v[148:151], v[216:219], v[12:15]
	v_mfma_f32_16x16x32_bf16 v[8:11], v[156:159], v[216:219], v[8:11]
	s_setprio 0
	s_setprio 1
	v_mfma_f32_16x16x32_bf16 v[56:59], v[160:163], v[176:179], v[56:59]
	v_mfma_f32_16x16x32_bf16 v[52:55], v[168:171], v[176:179], v[52:55]
	v_mfma_f32_16x16x32_bf16 v[40:43], v[160:163], v[184:187], v[40:43]
	v_mfma_f32_16x16x32_bf16 v[36:39], v[168:171], v[184:187], v[36:39]
	v_mfma_f32_16x16x32_bf16 v[20:23], v[160:163], v[204:207], v[20:23]
	v_mfma_f32_16x16x32_bf16 v[16:19], v[168:171], v[204:207], v[16:19]
	v_mfma_f32_16x16x32_bf16 v[4:7], v[160:163], v[212:215], v[4:7]
	v_mfma_f32_16x16x32_bf16 v[0:3], v[168:171], v[212:215], v[0:3]
	v_mfma_f32_16x16x32_bf16 v[56:59], v[164:167], v[180:183], v[56:59]
	v_mfma_f32_16x16x32_bf16 v[52:55], v[172:175], v[180:183], v[52:55]
	v_mfma_f32_16x16x32_bf16 v[40:43], v[164:167], v[188:191], v[40:43]
	v_mfma_f32_16x16x32_bf16 v[36:39], v[172:175], v[188:191], v[36:39]
	v_mfma_f32_16x16x32_bf16 v[20:23], v[164:167], v[208:211], v[20:23]
	v_mfma_f32_16x16x32_bf16 v[16:19], v[172:175], v[208:211], v[16:19]
	v_mfma_f32_16x16x32_bf16 v[4:7], v[164:167], v[216:219], v[4:7]
	v_mfma_f32_16x16x32_bf16 v[0:3], v[172:175], v[216:219], v[0:3]
	s_setprio 0
	s_barrier
	s_add_u32 vcc_lo, vcc_lo, 0x100
	s_addc_u32 vcc_hi, vcc_hi, 0
	v_lshl_add_u64 v[104:105], v[104:105], 0, s[10:11]
	v_lshl_add_u64 v[34:35], v[34:35], 0, s[10:11]
	s_cmp_ge_u32 s68, s62
	s_mov_b32 s46, s68
	s_cbranch_scc0 .LBB0_826
	s_andn2_b64 vcc, exec, s[42:43]
	s_cbranch_vccnz .LBB0_818
	v_mov_b32_e32 v0, 0
	s_mov_b32 s24, s34
	s_mov_b32 s18, s36
	s_mov_b64 s[6:7], s[50:51]
	s_mov_b64 s[30:31], s[90:91]
	s_mov_b32 s64, s65
	v_mov_b32_e32 v1, v0
	v_mov_b64_e32 v[2:3], 0
	v_mov_b64_e32 v[4:5], 0
	v_mov_b64_e32 v[6:7], 0
	v_mov_b64_e32 v[16:17], 0
	v_mov_b64_e32 v[18:19], 0
	v_mov_b64_e32 v[20:21], 0
	v_mov_b64_e32 v[22:23], 0
	v_mov_b64_e32 v[36:37], 0
	v_mov_b64_e32 v[38:39], 0
	v_mov_b64_e32 v[40:41], 0
	v_mov_b64_e32 v[42:43], 0
	v_mov_b64_e32 v[52:53], 0
	v_mov_b64_e32 v[54:55], 0
	v_mov_b64_e32 v[56:57], 0
	v_mov_b64_e32 v[58:59], 0
	v_mov_b64_e32 v[8:9], 0
	v_mov_b64_e32 v[10:11], 0
	v_mov_b64_e32 v[12:13], 0
	v_mov_b64_e32 v[14:15], 0
	v_mov_b64_e32 v[24:25], 0
	v_mov_b64_e32 v[26:27], 0
	v_mov_b64_e32 v[28:29], 0
	v_mov_b64_e32 v[30:31], 0
	v_mov_b64_e32 v[44:45], 0
	v_mov_b64_e32 v[46:47], 0
	v_mov_b64_e32 v[48:49], 0
	v_mov_b64_e32 v[50:51], 0
	v_mov_b64_e32 v[60:61], 0
	v_mov_b64_e32 v[62:63], 0
	v_mov_b64_e32 v[64:65], 0
	v_mov_b64_e32 v[66:67], 0
	v_mov_b64_e32 v[68:69], 0
	v_mov_b64_e32 v[70:71], 0
	v_mov_b64_e32 v[72:73], 0
	v_mov_b64_e32 v[74:75], 0
	v_mov_b64_e32 v[84:85], 0
	v_mov_b64_e32 v[86:87], 0
	v_mov_b64_e32 v[88:89], 0
	v_mov_b64_e32 v[90:91], 0
	v_mov_b64_e32 v[112:113], 0
	v_mov_b64_e32 v[114:115], 0
	v_mov_b64_e32 v[120:121], 0
	v_mov_b64_e32 v[122:123], 0
	v_mov_b64_e32 v[132:133], 0
	v_mov_b64_e32 v[134:135], 0
	v_mov_b64_e32 v[136:137], 0
	v_mov_b64_e32 v[138:139], 0
	v_mov_b64_e32 v[76:77], 0
	v_mov_b64_e32 v[78:79], 0
	v_mov_b64_e32 v[80:81], 0
	v_mov_b64_e32 v[82:83], 0
	v_mov_b64_e32 v[96:97], 0
	v_mov_b64_e32 v[98:99], 0
	v_mov_b64_e32 v[108:109], 0
	v_mov_b64_e32 v[110:111], 0
	v_mov_b64_e32 v[124:125], 0
	v_mov_b64_e32 v[126:127], 0
	v_mov_b64_e32 v[128:129], 0
	v_mov_b64_e32 v[130:131], 0
	v_mov_b64_e32 v[140:141], 0
	v_mov_b64_e32 v[142:143], 0
	v_mov_b64_e32 v[144:145], 0
	v_mov_b64_e32 v[146:147], 0
	s_branch .LBB0_818

; template <class Epi, class Sched, bool ALIGN_EPI = false, bool SP2 = false>
; __device__ __forceinline__ void gemm_phase(PG8_LAS unsigned char* lds, const Gemm g, const Sched& S, const Epi& E) {
;     ...
;     Unit cur, nxt; int ui = 0;
;     if (!S.next(0, cur)) return;
;     f32x4 acc[2][2][4][2];
; #pragma unroll
;     for (int a = 0; a < 2; ++a)
; #pragma unroll
;         for (int b = 0; b < 2; ++b)
; #pragma unroll
;             for (int m = 0; m < 4; ++m)
; #pragma unroll
;                 for (int n = 0; n < 2; ++n) acc[a][b][m][n] = (f32x4){0.f, 0.f, 0.f, 0.f};
;     ...
;         const bool has_next = S.next(ui + 1, nxt);
;         const char* nA = has_next ? (const char*)g.A + (size_t)nxt.pm * tstep : cA; const char* nB = has_next ? (const char*)g.Bt + (size_t)nxt.pn * tstep : cB;
;         for (int t = 0; t < nt; t += 2) {
;             const bool last = (t == nt - 2);
;             const char* a1 = cA + (size_t)(t + 1) * kstep;
;             const char* a2 = last ? nA : cA + (size_t)(t + 2) * kstep; const char* b2 = last ? nB : cB + (size_t)(t + 2) * kstep;
;             const char* a3 = a2 + kstep; const char* b3 = b2 + kstep;
.LBB0_935:
	s_ashr_i32 s27, s26, 31
	s_lshl_b64 s[28:29], s[26:27], 19
	s_add_u32 s28, s5, s28
	s_addc_u32 s29, s17, s29
	s_and_b64 s[30:31], s[40:41], exec
	s_cselect_b32 s27, s29, s37
	s_cselect_b32 s59, s28, s36
	s_ashr_i32 s25, s24, 31
	s_lshl_b64 s[30:31], s[24:25], 19
	s_add_u32 s30, s44, s30
	s_addc_u32 s31, s45, s31
	s_and_b64 s[46:47], s[40:41], exec
	s_cselect_b32 s25, s31, s43
	s_cselect_b32 s60, s30, s42
	s_add_u32 s36, s36, 0x40080
	s_addc_u32 s37, s37, 0
	s_add_u32 s61, s42, 0x100
	v_mov_b32_e32 v0, 0
	s_addc_u32 s62, s43, 0
	s_mov_b32 s63, -2
	v_mov_b32_e32 v1, v0
	v_mov_b64_e32 v[2:3], 0
	v_mov_b64_e32 v[4:5], 0
	v_mov_b64_e32 v[6:7], 0
	v_mov_b64_e32 v[16:17], 0
	v_mov_b64_e32 v[18:19], 0
	v_mov_b64_e32 v[20:21], 0
	v_mov_b64_e32 v[22:23], 0
	v_mov_b64_e32 v[34:35], 0
	v_mov_b64_e32 v[36:37], 0
	v_mov_b64_e32 v[38:39], 0
	v_mov_b64_e32 v[40:41], 0
	v_mov_b64_e32 v[50:51], 0
	v_mov_b64_e32 v[52:53], 0
	v_mov_b64_e32 v[54:55], 0
	v_mov_b64_e32 v[56:57], 0
	v_mov_b64_e32 v[8:9], 0
	v_mov_b64_e32 v[10:11], 0
	v_mov_b64_e32 v[12:13], 0
	v_mov_b64_e32 v[14:15], 0
	v_mov_b64_e32 v[24:25], 0
	v_mov_b64_e32 v[26:27], 0
	v_mov_b64_e32 v[28:29], 0
	v_mov_b64_e32 v[30:31], 0
	v_mov_b64_e32 v[42:43], 0
	v_mov_b64_e32 v[44:45], 0
	v_mov_b64_e32 v[46:47], 0
	v_mov_b64_e32 v[48:49], 0
	v_mov_b64_e32 v[58:59], 0
	v_mov_b64_e32 v[60:61], 0
	v_mov_b64_e32 v[62:63], 0
	v_mov_b64_e32 v[64:65], 0
	v_mov_b64_e32 v[66:67], 0
	v_mov_b64_e32 v[68:69], 0
	v_mov_b64_e32 v[70:71], 0
	v_mov_b64_e32 v[72:73], 0
	v_mov_b64_e32 v[82:83], 0
	v_mov_b64_e32 v[84:85], 0
	v_mov_b64_e32 v[86:87], 0
	v_mov_b64_e32 v[88:89], 0
	v_mov_b64_e32 v[98:99], 0
	v_mov_b64_e32 v[100:101], 0
	v_mov_b64_e32 v[102:103], 0
	v_mov_b64_e32 v[104:105], 0
	v_mov_b64_e32 v[114:115], 0
	v_mov_b64_e32 v[116:117], 0
	v_mov_b64_e32 v[118:119], 0
	v_mov_b64_e32 v[120:121], 0
	v_mov_b64_e32 v[74:75], 0
	v_mov_b64_e32 v[76:77], 0
	v_mov_b64_e32 v[78:79], 0
	v_mov_b64_e32 v[80:81], 0
	v_mov_b64_e32 v[90:91], 0
	v_mov_b64_e32 v[92:93], 0
	v_mov_b64_e32 v[94:95], 0
	v_mov_b64_e32 v[96:97], 0
	v_mov_b64_e32 v[106:107], 0
	v_mov_b64_e32 v[108:109], 0
	v_mov_b64_e32 v[110:111], 0
	v_mov_b64_e32 v[112:113], 0
	v_mov_b64_e32 v[122:123], 0
	v_mov_b64_e32 v[124:125], 0
	v_mov_b64_e32 v[126:127], 0
	v_mov_b64_e32 v[128:129], 0

; #define PG8_STAGE(bufoff, gbase, voff) do { _Pragma("unroll") for (int _i = 0; _i < 2; ++_i) \
;         __builtin_amdgcn_global_load_lds((const unsigned*)((const char*)(gbase) + (voff)[_i]), (PG8_LAS unsigned*)(lds + (bufoff) + ldsw + _i * 8192), 16, 0, 0); } while (0)
; #define PG8_LDA(dst, b, h) do { _Pragma("unroll") for (int m = 0; m < 4; ++m) _Pragma("unroll") for (int k = 0; k < 2; ++k) dst[m][k] = *(const PG8_LAS bf16x8*)(lds + PG8_SA(b, h) + aoff + m * 2048 + k * 1024); } while (0)
; #define PG8_LDB(dst, b, h) do { _Pragma("unroll") for (int n = 0; n < 2; ++n) _Pragma("unroll") for (int k = 0; k < 2; ++k) dst[n][k] = *(const PG8_LAS bf16x8*)(lds + PG8_SB(b, h) + boff + n * 2048 + k * 1024); } while (0)
; #define PG8_MMA(ai, bj, At, Bt) do { __builtin_amdgcn_s_setprio(1); _Pragma("unroll") for (int m = 0; m < 4; ++m) _Pragma("unroll") for (int n = 0; n < 2; ++n) _Pragma("unroll") for (int k = 0; k < 2; ++k) \
;         acc[ai][bj][m][n] = __builtin_amdgcn_mfma_f32_16x16x32_bf16(Bt[n][k], At[m][k], acc[ai][bj][m][n], 0, 0, 0); __builtin_amdgcn_s_setprio(0); } while (0)
; #define PG8_WAIT_V(n) asm volatile("s_waitcnt vmcnt(" #n ")" ::: "memory")
; #define PG8_WAIT_L(n) asm volatile("s_waitcnt lgkmcnt(" #n ")" ::: "memory")
; #define PG8_BAR __builtin_amdgcn_s_barrier()
; #define PG8_SCHED __builtin_amdgcn_sched_barrier(0)
; template <class Epi, class Sched, bool ALIGN_EPI = false, bool SP2 = false>
; __device__ __forceinline__ void gemm_phase(PG8_LAS unsigned char* lds, const Gemm g, const Sched& S, const Epi& E) {
;     ...
;             PG8_LDB(B0, 0, 0); PG8_LDB(B1, 0, 1); PG8_SCHED; PG8_LDA(At, 0, 0); PG8_STAGE(PG8_SA(1, 1), a1 + hstep, voffA);
;             PG8_WAIT_V(8); PG8_WAIT_L(0); PG8_BAR; PG8_MMA(0, 0, At, B0); PG8_MMA(0, 1, At, B1); PG8_BAR; PG8_SCHED;
;             PG8_LDA(At, 0, 1); PG8_STAGE(PG8_SB(0, 0), b2, voffB); PG8_STAGE(PG8_SB(0, 1), b2 + hstep, voffB); PG8_STAGE(PG8_SA(0, 0), a2, voffA);
;             PG8_WAIT_V(8); PG8_WAIT_L(0); PG8_BAR; PG8_MMA(1, 0, At, B0); PG8_MMA(1, 1, At, B1); PG8_BAR; PG8_SCHED;
.LBB0_1081:
	s_add_u32 s46, s6, s44
	s_addc_u32 s47, s7, s45
	s_add_u32 s46, s46, 0x100
	s_addc_u32 s47, s47, 0
	s_add_u32 s68, s66, s44
	s_addc_u32 s69, s67, s45
	s_add_i32 s70, 0, 0x10000
	s_cmpk_eq_i32 s44, 0x1500
	s_cselect_b32 s51, s37, s47
	s_cselect_b32 s50, s36, s46
	v_add_u32_e32 v33, s70, v142
	s_cselect_b32 s47, s35, s69
	s_cselect_b32 s46, s34, s68
	s_add_i32 s71, 0, 0x14000
	ds_read_b128 v[144:147], v33
	ds_read_b128 v[148:151], v33 offset:1024
	ds_read_b128 v[152:155], v33 offset:2048
	ds_read_b128 v[156:159], v33 offset:3072
	v_add_u32_e32 v33, s71, v142
	ds_read_b128 v[160:163], v33
	ds_read_b128 v[164:167], v33 offset:1024
	ds_read_b128 v[168:171], v33 offset:2048
	ds_read_b128 v[172:175], v33 offset:3072
	v_lshl_add_u64 v[220:221], v[34:35], 0, s[44:45]
	s_add_i32 m0, s56, 0xc000
	ds_read_b128 v[176:179], v143
	ds_read_b128 v[180:183], v143 offset:1024
	ds_read_b128 v[184:187], v143 offset:2048
	ds_read_b128 v[188:191], v143 offset:3072
	ds_read_b128 v[204:207], v143 offset:4096
	ds_read_b128 v[208:211], v143 offset:5120
	ds_read_b128 v[212:215], v143 offset:6144
	ds_read_b128 v[216:219], v143 offset:7168
	global_load_lds_dwordx4 v[220:221], off
	v_lshl_add_u64 v[220:221], v[140:141], 0, s[44:45]
	s_add_i32 m0, s56, 0xe000
	s_nop 0
	global_load_lds_dwordx4 v[220:221], off
	s_waitcnt vmcnt(8)
	s_waitcnt lgkmcnt(0)
	s_barrier
	s_setprio 1
	s_waitcnt lgkmcnt(0)
	v_mfma_f32_16x16x32_bf16 v[128:131], v[144:147], v[176:179], v[128:131]
	v_mfma_f32_16x16x32_bf16 v[124:127], v[152:155], v[176:179], v[124:127]
	v_mfma_f32_16x16x32_bf16 v[112:115], v[144:147], v[184:187], v[112:115]
	v_mfma_f32_16x16x32_bf16 v[108:111], v[152:155], v[184:187], v[108:111]
	v_mfma_f32_16x16x32_bf16 v[96:99], v[144:147], v[204:207], v[96:99]
	v_mfma_f32_16x16x32_bf16 v[92:95], v[152:155], v[204:207], v[92:95]
	v_mfma_f32_16x16x32_bf16 v[80:83], v[144:147], v[212:215], v[80:83]
	v_mfma_f32_16x16x32_bf16 v[76:79], v[152:155], v[212:215], v[76:79]
	v_mfma_f32_16x16x32_bf16 v[128:131], v[148:151], v[180:183], v[128:131]
	v_mfma_f32_16x16x32_bf16 v[124:127], v[156:159], v[180:183], v[124:127]
	v_mfma_f32_16x16x32_bf16 v[112:115], v[148:151], v[188:191], v[112:115]
	v_mfma_f32_16x16x32_bf16 v[108:111], v[156:159], v[188:191], v[108:111]
	v_mfma_f32_16x16x32_bf16 v[96:99], v[148:151], v[208:211], v[96:99]
	v_mfma_f32_16x16x32_bf16 v[92:95], v[156:159], v[208:211], v[92:95]
	v_mfma_f32_16x16x32_bf16 v[80:83], v[148:151], v[216:219], v[80:83]
	v_mfma_f32_16x16x32_bf16 v[76:79], v[156:159], v[216:219], v[76:79]
	s_setprio 0
	s_setprio 1
	v_mfma_f32_16x16x32_bf16 v[120:123], v[160:163], v[176:179], v[120:123]
	v_mfma_f32_16x16x32_bf16 v[116:119], v[168:171], v[176:179], v[116:119]
	v_mfma_f32_16x16x32_bf16 v[104:107], v[160:163], v[184:187], v[104:107]
	v_mfma_f32_16x16x32_bf16 v[100:103], v[168:171], v[184:187], v[100:103]
	v_mfma_f32_16x16x32_bf16 v[88:91], v[160:163], v[204:207], v[88:91]
	v_mfma_f32_16x16x32_bf16 v[84:87], v[168:171], v[204:207], v[84:87]
	v_mfma_f32_16x16x32_bf16 v[72:75], v[160:163], v[212:215], v[72:75]
	v_mfma_f32_16x16x32_bf16 v[68:71], v[168:171], v[212:215], v[68:71]
	v_mfma_f32_16x16x32_bf16 v[120:123], v[164:167], v[180:183], v[120:123]
	v_mfma_f32_16x16x32_bf16 v[116:119], v[172:175], v[180:183], v[116:119]
	v_mfma_f32_16x16x32_bf16 v[104:107], v[164:167], v[188:191], v[104:107]
	v_mfma_f32_16x16x32_bf16 v[100:103], v[172:175], v[188:191], v[100:103]
	v_mfma_f32_16x16x32_bf16 v[88:91], v[164:167], v[208:211], v[88:91]
	v_mfma_f32_16x16x32_bf16 v[84:87], v[172:175], v[208:211], v[84:87]
	v_mfma_f32_16x16x32_bf16 v[72:75], v[164:167], v[216:219], v[72:75]
	v_mfma_f32_16x16x32_bf16 v[68:71], v[172:175], v[216:219], v[68:71]
	s_setprio 0
	s_barrier
	s_add_i32 s68, s70, s55
	v_lshl_add_u64 v[220:221], s[46:47], 0, v[132:133]
	s_mov_b32 m0, s68
	ds_read_b128 v[176:179], v143 offset:16384
	ds_read_b128 v[180:183], v143 offset:17408
	ds_read_b128 v[184:187], v143 offset:18432
	ds_read_b128 v[188:191], v143 offset:19456
	ds_read_b128 v[204:207], v143 offset:20480
	ds_read_b128 v[208:211], v143 offset:21504
	ds_read_b128 v[212:215], v143 offset:22528
	ds_read_b128 v[216:219], v143 offset:23552
	global_load_lds_dwordx4 v[220:221], off
	s_add_i32 m0, s68, 0x2000
	s_add_u32 s68, s46, 0xb0000
	v_lshl_add_u64 v[222:223], s[46:47], 0, v[134:135]
	s_addc_u32 s69, s47, 0
	s_add_i32 s70, s71, s55
	global_load_lds_dwordx4 v[222:223], off
	v_lshl_add_u64 v[224:225], s[68:69], 0, v[132:133]
	s_mov_b32 m0, s70
	v_lshl_add_u64 v[226:227], s[50:51], 0, v[134:135]
	global_load_lds_dwordx4 v[224:225], off
	v_lshl_add_u64 v[224:225], s[68:69], 0, v[134:135]
	s_add_i32 m0, s70, 0x2000
	s_nop 0
	global_load_lds_dwordx4 v[224:225], off
	v_lshl_add_u64 v[224:225], s[50:51], 0, v[132:133]
	s_mov_b32 m0, s56
	s_nop 0
	global_load_lds_dwordx4 v[224:225], off
	s_mov_b32 m0, s57
	s_nop 0
	global_load_lds_dwordx4 v[226:227], off
	s_waitcnt vmcnt(8)
	s_waitcnt lgkmcnt(0)
	s_barrier
; #define PG8_STAGE(bufoff, gbase, voff) do { _Pragma("unroll") for (int _i = 0; _i < 2; ++_i) \
;         __builtin_amdgcn_global_load_lds((const unsigned*)((const char*)(gbase) + (voff)[_i]), (PG8_LAS unsigned*)(lds + (bufoff) + ldsw + _i * 8192), 16, 0, 0); } while (0)
; #define PG8_LDA(dst, b, h) do { _Pragma("unroll") for (int m = 0; m < 4; ++m) _Pragma("unroll") for (int k = 0; k < 2; ++k) dst[m][k] = *(const PG8_LAS bf16x8*)(lds + PG8_SA(b, h) + aoff + m * 2048 + k * 1024); } while (0)
; #define PG8_LDB(dst, b, h) do { _Pragma("unroll") for (int n = 0; n < 2; ++n) _Pragma("unroll") for (int k = 0; k < 2; ++k) dst[n][k] = *(const PG8_LAS bf16x8*)(lds + PG8_SB(b, h) + boff + n * 2048 + k * 1024); } while (0)
; #define PG8_MMA(ai, bj, At, Bt) do { __builtin_amdgcn_s_setprio(1); _Pragma("unroll") for (int m = 0; m < 4; ++m) _Pragma("unroll") for (int n = 0; n < 2; ++n) _Pragma("unroll") for (int k = 0; k < 2; ++k) \
;         acc[ai][bj][m][n] = __builtin_amdgcn_mfma_f32_16x16x32_bf16(Bt[n][k], At[m][k], acc[ai][bj][m][n], 0, 0, 0); __builtin_amdgcn_s_setprio(0); } while (0)
; #define PG8_WAIT_V(n) asm volatile("s_waitcnt vmcnt(" #n ")" ::: "memory")
; #define PG8_WAIT_L(n) asm volatile("s_waitcnt lgkmcnt(" #n ")" ::: "memory")
; #define PG8_BAR __builtin_amdgcn_s_barrier()
; #define PG8_SCHED __builtin_amdgcn_sched_barrier(0)
; template <class Epi, class Sched, bool ALIGN_EPI = false, bool SP2 = false>
; __device__ __forceinline__ void gemm_phase(PG8_LAS unsigned char* lds, const Gemm g, const Sched& S, const Epi& E) {
;     ...
;             PG8_WAIT_V(8); PG8_WAIT_L(0); PG8_BAR; PG8_MMA(1, 0, At, B0); PG8_MMA(1, 1, At, B1); PG8_BAR; PG8_SCHED;
;             PG8_LDB(B0, 1, 0); PG8_LDB(B1, 1, 1); PG8_SCHED; PG8_LDA(At, 1, 0); PG8_STAGE(PG8_SA(0, 1), a2 + hstep, voffA);
;             PG8_WAIT_V(8); PG8_WAIT_L(0); PG8_BAR; PG8_MMA(0, 0, At, B0); PG8_MMA(0, 1, At, B1); PG8_BAR; PG8_SCHED;
	s_setprio 1
	s_waitcnt lgkmcnt(0)
	v_mfma_f32_16x16x32_bf16 v[64:67], v[144:147], v[176:179], v[64:67]
	v_mfma_f32_16x16x32_bf16 v[60:63], v[152:155], v[176:179], v[60:63]
	v_mfma_f32_16x16x32_bf16 v[48:51], v[144:147], v[184:187], v[48:51]
	v_mfma_f32_16x16x32_bf16 v[44:47], v[152:155], v[184:187], v[44:47]
	v_mfma_f32_16x16x32_bf16 v[28:31], v[144:147], v[204:207], v[28:31]
	v_mfma_f32_16x16x32_bf16 v[24:27], v[152:155], v[204:207], v[24:27]
	v_mfma_f32_16x16x32_bf16 v[12:15], v[144:147], v[212:215], v[12:15]
	v_mfma_f32_16x16x32_bf16 v[8:11], v[152:155], v[212:215], v[8:11]
	v_mfma_f32_16x16x32_bf16 v[64:67], v[148:151], v[180:183], v[64:67]
	v_mfma_f32_16x16x32_bf16 v[60:63], v[156:159], v[180:183], v[60:63]
	v_mfma_f32_16x16x32_bf16 v[48:51], v[148:151], v[188:191], v[48:51]
	v_mfma_f32_16x16x32_bf16 v[44:47], v[156:159], v[188:191], v[44:47]
	v_mfma_f32_16x16x32_bf16 v[28:31], v[148:151], v[208:211], v[28:31]
	v_mfma_f32_16x16x32_bf16 v[24:27], v[156:159], v[208:211], v[24:27]
	v_mfma_f32_16x16x32_bf16 v[12:15], v[148:151], v[216:219], v[12:15]
	v_mfma_f32_16x16x32_bf16 v[8:11], v[156:159], v[216:219], v[8:11]
	s_setprio 0
	s_setprio 1
	v_mfma_f32_16x16x32_bf16 v[56:59], v[160:163], v[176:179], v[56:59]
	v_mfma_f32_16x16x32_bf16 v[52:55], v[168:171], v[176:179], v[52:55]
	v_mfma_f32_16x16x32_bf16 v[40:43], v[160:163], v[184:187], v[40:43]
	v_mfma_f32_16x16x32_bf16 v[36:39], v[168:171], v[184:187], v[36:39]
	v_mfma_f32_16x16x32_bf16 v[20:23], v[160:163], v[204:207], v[20:23]
	v_mfma_f32_16x16x32_bf16 v[16:19], v[168:171], v[204:207], v[16:19]
	v_mfma_f32_16x16x32_bf16 v[4:7], v[160:163], v[212:215], v[4:7]
	v_mfma_f32_16x16x32_bf16 v[0:3], v[168:171], v[212:215], v[0:3]
	v_mfma_f32_16x16x32_bf16 v[56:59], v[164:167], v[180:183], v[56:59]
	v_mfma_f32_16x16x32_bf16 v[52:55], v[172:175], v[180:183], v[52:55]
	v_mfma_f32_16x16x32_bf16 v[40:43], v[164:167], v[188:191], v[40:43]
	v_mfma_f32_16x16x32_bf16 v[36:39], v[172:175], v[188:191], v[36:39]
	v_mfma_f32_16x16x32_bf16 v[20:23], v[164:167], v[208:211], v[20:23]
	v_mfma_f32_16x16x32_bf16 v[16:19], v[172:175], v[208:211], v[16:19]
	v_mfma_f32_16x16x32_bf16 v[4:7], v[164:167], v[216:219], v[4:7]
	v_mfma_f32_16x16x32_bf16 v[0:3], v[172:175], v[216:219], v[0:3]
	s_setprio 0
	s_barrier
	s_add_i32 s68, 0, 0x18000
	v_add_u32_e32 v33, s68, v142
	s_add_i32 s69, 0, 0x1c000
	ds_read_b128 v[144:147], v33
	ds_read_b128 v[148:151], v33 offset:1024
	ds_read_b128 v[152:155], v33 offset:2048
	ds_read_b128 v[156:159], v33 offset:3072
	v_add_u32_e32 v33, s69, v142
	ds_read_b128 v[160:163], v33
	ds_read_b128 v[164:167], v33 offset:1024
	ds_read_b128 v[168:171], v33 offset:2048
	ds_read_b128 v[172:175], v33 offset:3072
	s_add_u32 s50, s50, 0xb0000
	s_addc_u32 s51, s51, 0
	s_mov_b32 m0, s58
	v_lshl_add_u64 v[238:239], s[50:51], 0, v[132:133]
	ds_read_b128 v[176:179], v143 offset:32768
	ds_read_b128 v[180:183], v143 offset:33792
	ds_read_b128 v[184:187], v143 offset:34816
	ds_read_b128 v[188:191], v143 offset:35840
	ds_read_b128 v[204:207], v143 offset:36864
	ds_read_b128 v[208:211], v143 offset:37888
	ds_read_b128 v[212:215], v143 offset:38912
	ds_read_b128 v[216:219], v143 offset:39936
	global_load_lds_dwordx4 v[238:239], off
	v_lshl_add_u64 v[238:239], s[50:51], 0, v[134:135]
	s_mov_b32 m0, s59
	s_nop 0
	global_load_lds_dwordx4 v[238:239], off
	s_waitcnt vmcnt(8)
	s_waitcnt lgkmcnt(0)
	s_barrier
	s_setprio 1
	s_waitcnt lgkmcnt(0)
	v_mfma_f32_16x16x32_bf16 v[128:131], v[144:147], v[176:179], v[128:131]
	v_mfma_f32_16x16x32_bf16 v[124:127], v[152:155], v[176:179], v[124:127]
	v_mfma_f32_16x16x32_bf16 v[112:115], v[144:147], v[184:187], v[112:115]
	v_mfma_f32_16x16x32_bf16 v[108:111], v[152:155], v[184:187], v[108:111]
	v_mfma_f32_16x16x32_bf16 v[96:99], v[144:147], v[204:207], v[96:99]
	v_mfma_f32_16x16x32_bf16 v[92:95], v[152:155], v[204:207], v[92:95]
	v_mfma_f32_16x16x32_bf16 v[80:83], v[144:147], v[212:215], v[80:83]
	v_mfma_f32_16x16x32_bf16 v[76:79], v[152:155], v[212:215], v[76:79]
	v_mfma_f32_16x16x32_bf16 v[128:131], v[148:151], v[180:183], v[128:131]
	v_mfma_f32_16x16x32_bf16 v[124:127], v[156:159], v[180:183], v[124:127]
	v_mfma_f32_16x16x32_bf16 v[112:115], v[148:151], v[188:191], v[112:115]
	v_mfma_f32_16x16x32_bf16 v[108:111], v[156:159], v[188:191], v[108:111]
	v_mfma_f32_16x16x32_bf16 v[96:99], v[148:151], v[208:211], v[96:99]
	v_mfma_f32_16x16x32_bf16 v[92:95], v[156:159], v[208:211], v[92:95]
	v_mfma_f32_16x16x32_bf16 v[80:83], v[148:151], v[216:219], v[80:83]
	v_mfma_f32_16x16x32_bf16 v[76:79], v[156:159], v[216:219], v[76:79]
	s_setprio 0
	s_setprio 1
	v_mfma_f32_16x16x32_bf16 v[120:123], v[160:163], v[176:179], v[120:123]
	v_mfma_f32_16x16x32_bf16 v[116:119], v[168:171], v[176:179], v[116:119]
	v_mfma_f32_16x16x32_bf16 v[104:107], v[160:163], v[184:187], v[104:107]
	v_mfma_f32_16x16x32_bf16 v[100:103], v[168:171], v[184:187], v[100:103]
	v_mfma_f32_16x16x32_bf16 v[88:91], v[160:163], v[204:207], v[88:91]
	v_mfma_f32_16x16x32_bf16 v[84:87], v[168:171], v[204:207], v[84:87]
	v_mfma_f32_16x16x32_bf16 v[72:75], v[160:163], v[212:215], v[72:75]
	v_mfma_f32_16x16x32_bf16 v[68:71], v[168:171], v[212:215], v[68:71]
	v_mfma_f32_16x16x32_bf16 v[120:123], v[164:167], v[180:183], v[120:123]
	v_mfma_f32_16x16x32_bf16 v[116:119], v[172:175], v[180:183], v[116:119]
	v_mfma_f32_16x16x32_bf16 v[104:107], v[164:167], v[188:191], v[104:107]
	v_mfma_f32_16x16x32_bf16 v[100:103], v[172:175], v[188:191], v[100:103]
	v_mfma_f32_16x16x32_bf16 v[88:91], v[164:167], v[208:211], v[88:91]
	v_mfma_f32_16x16x32_bf16 v[84:87], v[172:175], v[208:211], v[84:87]
	v_mfma_f32_16x16x32_bf16 v[72:75], v[164:167], v[216:219], v[72:75]
	v_mfma_f32_16x16x32_bf16 v[68:71], v[172:175], v[216:219], v[68:71]
	s_setprio 0
	s_barrier
; #define PG8_STAGE(bufoff, gbase, voff) do { _Pragma("unroll") for (int _i = 0; _i < 2; ++_i) \
;         __builtin_amdgcn_global_load_lds((const unsigned*)((const char*)(gbase) + (voff)[_i]), (PG8_LAS unsigned*)(lds + (bufoff) + ldsw + _i * 8192), 16, 0, 0); } while (0)
; #define PG8_LDA(dst, b, h) do { _Pragma("unroll") for (int m = 0; m < 4; ++m) _Pragma("unroll") for (int k = 0; k < 2; ++k) dst[m][k] = *(const PG8_LAS bf16x8*)(lds + PG8_SA(b, h) + aoff + m * 2048 + k * 1024); } while (0)
; #define PG8_MMA(ai, bj, At, Bt) do { __builtin_amdgcn_s_setprio(1); _Pragma("unroll") for (int m = 0; m < 4; ++m) _Pragma("unroll") for (int n = 0; n < 2; ++n) _Pragma("unroll") for (int k = 0; k < 2; ++k) \
;         acc[ai][bj][m][n] = __builtin_amdgcn_mfma_f32_16x16x32_bf16(Bt[n][k], At[m][k], acc[ai][bj][m][n], 0, 0, 0); __builtin_amdgcn_s_setprio(0); } while (0)
; #define PG8_WAIT_V(n) asm volatile("s_waitcnt vmcnt(" #n ")" ::: "memory")
; #define PG8_WAIT_L(n) asm volatile("s_waitcnt lgkmcnt(" #n ")" ::: "memory")
; #define PG8_BAR __builtin_amdgcn_s_barrier()
; #define PG8_SCHED __builtin_amdgcn_sched_barrier(0)
; template <class Epi, class Sched, bool ALIGN_EPI = false, bool SP2 = false>
; __device__ __forceinline__ void gemm_phase(PG8_LAS unsigned char* lds, const Gemm g, const Sched& S, const Epi& E) {
;     ...
;             PG8_LDA(At, 1, 1); PG8_STAGE(PG8_SB(1, 0), b3, voffB); PG8_STAGE(PG8_SB(1, 1), b3 + hstep, voffB); PG8_STAGE(PG8_SA(1, 0), a3, voffA);
;             PG8_WAIT_V(8); PG8_WAIT_L(0); PG8_BAR; PG8_MMA(1, 0, At, B0); PG8_MMA(1, 1, At, B1); PG8_BAR; PG8_SCHED;
;     ...
;         if (!has_next) break;
; #pragma unroll
;         for (int a = 0; a < 2; ++a)
; #pragma unroll
;             for (int b = 0; b < 2; ++b)
; #pragma unroll
;                 for (int m = 0; m < 4; ++m)
; #pragma unroll
;                     for (int n = 0; n < 2; ++n) acc[a][b][m][n] = (f32x4){0.f, 0.f, 0.f, 0.f};
;         cur = nxt; cA = nA; cB = nB; ++ui;
;         if constexpr (ALIGN_EPI) { if (wr == 1) PG8_BAR; }
	s_add_i32 s50, s68, s55
	v_lshl_add_u64 v[220:221], v[220:221], 0, s[8:9]
	s_mov_b32 m0, s50
	ds_read_b128 v[176:179], v143 offset:49152
	ds_read_b128 v[180:183], v143 offset:50176
	ds_read_b128 v[184:187], v143 offset:51200
	ds_read_b128 v[188:191], v143 offset:52224
	ds_read_b128 v[204:207], v143 offset:53248
	ds_read_b128 v[208:211], v143 offset:54272
	ds_read_b128 v[212:215], v143 offset:55296
	ds_read_b128 v[216:219], v143 offset:56320
	global_load_lds_dwordx4 v[220:221], off
	s_add_i32 m0, s50, 0x2000
	s_add_u32 s46, s46, 0xb0080
	v_lshl_add_u64 v[220:221], v[222:223], 0, s[8:9]
	s_addc_u32 s47, s47, 0
	s_add_i32 s50, s69, s55
	global_load_lds_dwordx4 v[220:221], off
	v_lshl_add_u64 v[220:221], s[46:47], 0, v[132:133]
	s_mov_b32 m0, s50
	s_nop 0
	global_load_lds_dwordx4 v[220:221], off
	v_lshl_add_u64 v[220:221], s[46:47], 0, v[134:135]
	s_add_i32 m0, s50, 0x2000
	s_nop 0
	global_load_lds_dwordx4 v[220:221], off
	v_lshl_add_u64 v[220:221], v[224:225], 0, s[8:9]
	s_mov_b32 m0, s60
	s_nop 0
	global_load_lds_dwordx4 v[220:221], off
	v_lshl_add_u64 v[220:221], v[226:227], 0, s[8:9]
	s_mov_b32 m0, s61
	s_nop 0
	global_load_lds_dwordx4 v[220:221], off
	s_waitcnt vmcnt(8)
	s_waitcnt lgkmcnt(0)
	s_barrier
	s_setprio 1
	s_waitcnt lgkmcnt(0)
	v_mfma_f32_16x16x32_bf16 v[64:67], v[144:147], v[176:179], v[64:67]
	v_mfma_f32_16x16x32_bf16 v[60:63], v[152:155], v[176:179], v[60:63]
	v_mfma_f32_16x16x32_bf16 v[48:51], v[144:147], v[184:187], v[48:51]
	v_mfma_f32_16x16x32_bf16 v[44:47], v[152:155], v[184:187], v[44:47]
	v_mfma_f32_16x16x32_bf16 v[28:31], v[144:147], v[204:207], v[28:31]
	v_mfma_f32_16x16x32_bf16 v[24:27], v[152:155], v[204:207], v[24:27]
	v_mfma_f32_16x16x32_bf16 v[12:15], v[144:147], v[212:215], v[12:15]
	v_mfma_f32_16x16x32_bf16 v[8:11], v[152:155], v[212:215], v[8:11]
	v_mfma_f32_16x16x32_bf16 v[64:67], v[148:151], v[180:183], v[64:67]
	v_mfma_f32_16x16x32_bf16 v[60:63], v[156:159], v[180:183], v[60:63]
	v_mfma_f32_16x16x32_bf16 v[48:51], v[148:151], v[188:191], v[48:51]
	v_mfma_f32_16x16x32_bf16 v[44:47], v[156:159], v[188:191], v[44:47]
	v_mfma_f32_16x16x32_bf16 v[28:31], v[148:151], v[208:211], v[28:31]
	v_mfma_f32_16x16x32_bf16 v[24:27], v[156:159], v[208:211], v[24:27]
	v_mfma_f32_16x16x32_bf16 v[12:15], v[148:151], v[216:219], v[12:15]
	v_mfma_f32_16x16x32_bf16 v[8:11], v[156:159], v[216:219], v[8:11]
	s_setprio 0
	s_setprio 1
	v_mfma_f32_16x16x32_bf16 v[56:59], v[160:163], v[176:179], v[56:59]
	v_mfma_f32_16x16x32_bf16 v[52:55], v[168:171], v[176:179], v[52:55]
	v_mfma_f32_16x16x32_bf16 v[40:43], v[160:163], v[184:187], v[40:43]
	v_mfma_f32_16x16x32_bf16 v[36:39], v[168:171], v[184:187], v[36:39]
	v_mfma_f32_16x16x32_bf16 v[20:23], v[160:163], v[204:207], v[20:23]
	v_mfma_f32_16x16x32_bf16 v[16:19], v[168:171], v[204:207], v[16:19]
	v_mfma_f32_16x16x32_bf16 v[4:7], v[160:163], v[212:215], v[4:7]
	v_mfma_f32_16x16x32_bf16 v[0:3], v[168:171], v[212:215], v[0:3]
	v_mfma_f32_16x16x32_bf16 v[56:59], v[164:167], v[180:183], v[56:59]
	v_mfma_f32_16x16x32_bf16 v[52:55], v[172:175], v[180:183], v[52:55]
	v_mfma_f32_16x16x32_bf16 v[40:43], v[164:167], v[188:191], v[40:43]
	v_mfma_f32_16x16x32_bf16 v[36:39], v[172:175], v[188:191], v[36:39]
	v_mfma_f32_16x16x32_bf16 v[20:23], v[164:167], v[208:211], v[20:23]
	v_mfma_f32_16x16x32_bf16 v[16:19], v[172:175], v[208:211], v[16:19]
	v_mfma_f32_16x16x32_bf16 v[4:7], v[164:167], v[216:219], v[4:7]
	v_mfma_f32_16x16x32_bf16 v[0:3], v[172:175], v[216:219], v[0:3]
	s_setprio 0
	s_barrier
	s_add_i32 s94, s94, 2
	s_add_u32 s44, s44, 0x100
	s_addc_u32 s45, s45, 0
	s_cmp_gt_u32 s94, 41
	s_cbranch_scc0 .LBB0_1081
	s_add_u32 s44, s66, 0xffffff00
	s_addc_u32 s45, s67, -1
	s_and_b64 vcc, exec, s[42:43]
	s_cbranch_vccnz .LBB0_1084
	v_mov_b32_e32 v0, 0
	s_mov_b32 s28, s63
	s_mov_b32 s90, s64
	s_mov_b64 s[6:7], s[36:37]
	s_mov_b32 s62, s65
	v_mov_b32_e32 v1, v0
	v_mov_b64_e32 v[2:3], 0
	v_mov_b64_e32 v[4:5], 0
	v_mov_b64_e32 v[6:7], 0
	v_mov_b64_e32 v[16:17], 0
	v_mov_b64_e32 v[18:19], 0
	v_mov_b64_e32 v[20:21], 0
	v_mov_b64_e32 v[22:23], 0
	v_mov_b64_e32 v[36:37], 0
	v_mov_b64_e32 v[38:39], 0
	v_mov_b64_e32 v[40:41], 0
	v_mov_b64_e32 v[42:43], 0
	v_mov_b64_e32 v[52:53], 0
	v_mov_b64_e32 v[54:55], 0
	v_mov_b64_e32 v[56:57], 0
	v_mov_b64_e32 v[58:59], 0
	v_mov_b64_e32 v[8:9], 0
	v_mov_b64_e32 v[10:11], 0
	v_mov_b64_e32 v[12:13], 0
	v_mov_b64_e32 v[14:15], 0
	v_mov_b64_e32 v[24:25], 0
	v_mov_b64_e32 v[26:27], 0
	v_mov_b64_e32 v[28:29], 0
	v_mov_b64_e32 v[30:31], 0
	v_mov_b64_e32 v[44:45], 0
	v_mov_b64_e32 v[46:47], 0
	v_mov_b64_e32 v[48:49], 0
	v_mov_b64_e32 v[50:51], 0
	v_mov_b64_e32 v[60:61], 0
	v_mov_b64_e32 v[62:63], 0
	v_mov_b64_e32 v[64:65], 0
	v_mov_b64_e32 v[66:67], 0
	v_mov_b64_e32 v[68:69], 0
	v_mov_b64_e32 v[70:71], 0
	v_mov_b64_e32 v[72:73], 0
	v_mov_b64_e32 v[74:75], 0
	v_mov_b64_e32 v[84:85], 0
	v_mov_b64_e32 v[86:87], 0
	v_mov_b64_e32 v[88:89], 0
	v_mov_b64_e32 v[90:91], 0
	v_mov_b64_e32 v[100:101], 0
	v_mov_b64_e32 v[102:103], 0
	v_mov_b64_e32 v[104:105], 0
	v_mov_b64_e32 v[106:107], 0
	v_mov_b64_e32 v[116:117], 0
	v_mov_b64_e32 v[118:119], 0
	v_mov_b64_e32 v[120:121], 0
	v_mov_b64_e32 v[122:123], 0
	v_mov_b64_e32 v[76:77], 0
	v_mov_b64_e32 v[78:79], 0
	v_mov_b64_e32 v[80:81], 0
	v_mov_b64_e32 v[82:83], 0
	v_mov_b64_e32 v[92:93], 0
	v_mov_b64_e32 v[94:95], 0
	v_mov_b64_e32 v[96:97], 0
	v_mov_b64_e32 v[98:99], 0
	v_mov_b64_e32 v[108:109], 0
	v_mov_b64_e32 v[110:111], 0
	v_mov_b64_e32 v[112:113], 0
	v_mov_b64_e32 v[114:115], 0
	v_mov_b64_e32 v[124:125], 0
	v_mov_b64_e32 v[126:127], 0
	v_mov_b64_e32 v[128:129], 0
	v_mov_b64_e32 v[130:131], 0
	s_andn2_b64 vcc, exec, s[40:41]
	s_cbranch_vccnz .LBB0_1085
	s_branch .LBB0_1086
